# v7 + G1 GEMM: MFMA operands swapped (transposed accumulators) and hand-written epilogue with 8-byte stores instead of 128 masked 2-byte stores
# speedup vs baseline: 1.0130x; 1.0130x over previous
; #define STAGE8(P, BASE, br, kt) do { const bf16_t* _g = (BASE) + (size_t)(br) * K + (kt) * 64; \
;     _Pragma("unroll") for (int _i = 0; _i < 2; ++_i) \
;       __builtin_amdgcn_global_load_lds((glb_u32*)(_g + goff0 + _i * 64 * K), (lds_u32*)((char*)(P) + tid * 16 + _i * 8192), 16, 0, 0); } while (0)
; #define LDA8(dst, b, h) _Pragma("unroll") for (int m = 0; m < 4; ++m) _Pragma("unroll") for (int k = 0; k < 2; ++k) \
;     dst[m][k] = *reinterpret_cast<const bf16x8*>((const char*)SA8(b, h) + lds_byte(wr * 64 + m * 16 + fr, k * 32 + fq * 8))
; #define LDB8(dst, b, h) _Pragma("unroll") for (int n = 0; n < 2; ++n) _Pragma("unroll") for (int k = 0; k < 2; ++k) \
;     dst[n][k] = *reinterpret_cast<const bf16x8*>((const char*)SB8(b, h) + lds_byte(wc * 32 + n * 16 + fr, k * 32 + fq * 8))
; #define MMA8(ai, bj, Af, Bf) do { __builtin_amdgcn_s_setprio(3); \
;     _Pragma("unroll") for (int m = 0; m < 4; ++m) _Pragma("unroll") for (int n = 0; n < 2; ++n) _Pragma("unroll") for (int k = 0; k < 2; ++k) \
;       acc[ai][bj][m][n] = __builtin_amdgcn_mfma_f32_16x16x32_bf16(Af[m][k], Bf[n][k], acc[ai][bj][m][n], 0, 0, 0); \
;     __builtin_amdgcn_s_setprio(0); } while (0)
; #define WAIT_L8(n) asm volatile("s_waitcnt lgkmcnt(" #n ")" ::: "memory")
; #define BAR8 __builtin_amdgcn_s_barrier()
; #define SCHED8 __builtin_amdgcn_sched_barrier(0)
; template <int EPI>
; __device__ __forceinline__ void gemm_tile8p(const bf16_t* __restrict__ Ag, const bf16_t* __restrict__ Bg, int K, int nt, int brow, int bcol,
;                                             char* smem, void* outp, int ldo, int nvalid, int rowoff, int rowlim) {
;     ...
;     LDB8(B0, 0, 0); SCHED8; LDA8(At, 0, 0); STAGE8(SA8(1, 1), Ag, brow + HALF, t + 1);
;     WAIT_L8(8); BAR8; WAIT_L8(0); MMA8(0, 0, At, B0); BAR8; SCHED8;
;     LDB8(B1, 0, 1); STAGE8(SB8(0, 0), Bg, bcol, t + 2);
;     BAR8; WAIT_L8(0); MMA8(0, 1, At, B1); BAR8;
;     LDA8(At, 0, 1); STAGE8(SA8(0, 0), Ag, brow, t + 2);
;     BAR8; WAIT_L8(0); MMA8(1, 0, At, B0); BAR8; SCHED8;
.LBB0_1066:
	ds_read_b128 v[164:167], v161
	ds_read_b128 v[168:171], v161 offset:1024
	ds_read_b128 v[172:175], v161 offset:2048
	ds_read_b128 v[176:179], v161 offset:3072
	v_add_u32_e32 v162, 0xc000, v137
	v_lshl_add_u64 v[248:249], s[40:41], 0, v[130:131]
	v_readfirstlane_b32 s3, v162
	v_add_u32_e32 v163, 0xe000, v137
	v_lshl_add_u64 v[232:233], v[248:249], 0, s[4:5]
	s_mov_b32 m0, s3
	v_readfirstlane_b32 s3, v163
	ds_read_b128 v[180:183], v141
	ds_read_b128 v[184:187], v141 offset:1024
	ds_read_b128 v[188:191], v140
	ds_read_b128 v[192:195], v140 offset:1024
	ds_read_b128 v[196:199], v139
	ds_read_b128 v[200:203], v139 offset:1024
	ds_read_b128 v[204:207], v138
	ds_read_b128 v[208:211], v138 offset:1024
	global_load_lds_dwordx4 v[232:233], off
	v_lshl_add_u64 v[232:233], v[248:249], 0, s[8:9]
	s_mov_b32 m0, s3
	s_nop 0
	global_load_lds_dwordx4 v[232:233], off
	s_waitcnt lgkmcnt(8)
	s_barrier
	s_waitcnt lgkmcnt(0)
	s_setprio 3
	s_waitcnt lgkmcnt(0)
	v_mfma_f32_16x16x32_bf16 v[124:127], v[164:167], v[180:183], v[124:127]
	v_mfma_f32_16x16x32_bf16 v[120:123], v[172:175], v[180:183], v[120:123]
	v_mfma_f32_16x16x32_bf16 v[116:119], v[164:167], v[188:191], v[116:119]
	v_mfma_f32_16x16x32_bf16 v[112:115], v[172:175], v[188:191], v[112:115]
	v_mfma_f32_16x16x32_bf16 v[108:111], v[164:167], v[196:199], v[108:111]
	v_mfma_f32_16x16x32_bf16 v[104:107], v[172:175], v[196:199], v[104:107]
	v_mfma_f32_16x16x32_bf16 v[100:103], v[164:167], v[204:207], v[100:103]
	v_mfma_f32_16x16x32_bf16 v[96:99], v[172:175], v[204:207], v[96:99]
	v_mfma_f32_16x16x32_bf16 v[124:127], v[168:171], v[184:187], v[124:127]
	v_mfma_f32_16x16x32_bf16 v[120:123], v[176:179], v[184:187], v[120:123]
	v_mfma_f32_16x16x32_bf16 v[116:119], v[168:171], v[192:195], v[116:119]
	v_mfma_f32_16x16x32_bf16 v[112:115], v[176:179], v[192:195], v[112:115]
	v_mfma_f32_16x16x32_bf16 v[108:111], v[168:171], v[200:203], v[108:111]
	v_mfma_f32_16x16x32_bf16 v[104:107], v[176:179], v[200:203], v[104:107]
	v_mfma_f32_16x16x32_bf16 v[100:103], v[168:171], v[208:211], v[100:103]
	v_mfma_f32_16x16x32_bf16 v[96:99], v[176:179], v[208:211], v[96:99]
	s_setprio 0
	s_barrier
	v_lshl_add_u64 v[250:251], s[42:43], 0, v[130:131]
	v_readfirstlane_b32 s3, v142
	v_lshl_add_u64 v[230:231], v[250:251], 0, s[12:13]
	s_mov_b32 m0, s3
	v_readfirstlane_b32 s3, v143
	ds_read_b128 v[232:235], v158
	ds_read_b128 v[236:239], v158 offset:1024
	ds_read_b128 v[240:243], v158 offset:2048
	ds_read_b128 v[244:247], v158 offset:3072
	global_load_lds_dwordx4 v[230:231], off
	v_lshl_add_u64 v[230:231], v[250:251], 0, s[14:15]
	s_mov_b32 m0, s3
	s_nop 0
	global_load_lds_dwordx4 v[230:231], off
	s_barrier
	s_waitcnt lgkmcnt(0)
	s_setprio 3
	s_waitcnt lgkmcnt(0)
	v_mfma_f32_16x16x32_bf16 v[92:95], v[232:235], v[180:183], v[92:95]
	v_mfma_f32_16x16x32_bf16 v[88:91], v[240:243], v[180:183], v[88:91]
	v_mfma_f32_16x16x32_bf16 v[84:87], v[232:235], v[188:191], v[84:87]
	v_mfma_f32_16x16x32_bf16 v[80:83], v[240:243], v[188:191], v[80:83]
	v_mfma_f32_16x16x32_bf16 v[76:79], v[232:235], v[196:199], v[76:79]
	v_mfma_f32_16x16x32_bf16 v[72:75], v[240:243], v[196:199], v[72:75]
	v_mfma_f32_16x16x32_bf16 v[68:71], v[232:235], v[204:207], v[68:71]
	v_mfma_f32_16x16x32_bf16 v[64:67], v[240:243], v[204:207], v[64:67]
	v_mfma_f32_16x16x32_bf16 v[92:95], v[236:239], v[184:187], v[92:95]
	v_mfma_f32_16x16x32_bf16 v[88:91], v[244:247], v[184:187], v[88:91]
	v_mfma_f32_16x16x32_bf16 v[84:87], v[236:239], v[192:195], v[84:87]
	v_mfma_f32_16x16x32_bf16 v[80:83], v[244:247], v[192:195], v[80:83]
	v_mfma_f32_16x16x32_bf16 v[76:79], v[236:239], v[200:203], v[76:79]
	v_mfma_f32_16x16x32_bf16 v[72:75], v[244:247], v[200:203], v[72:75]
	v_mfma_f32_16x16x32_bf16 v[68:71], v[236:239], v[208:211], v[68:71]
	v_mfma_f32_16x16x32_bf16 v[64:67], v[244:247], v[208:211], v[64:67]
	s_setprio 0
	v_readfirstlane_b32 s3, v137
	v_lshl_add_u64 v[230:231], v[248:249], 0, s[28:29]
	s_mov_b32 m0, s3
	v_readfirstlane_b32 s3, v145
	s_barrier
	ds_read_b128 v[180:183], v141 offset:16384
	ds_read_b128 v[184:187], v141 offset:17408
	ds_read_b128 v[188:191], v140 offset:16384
	ds_read_b128 v[192:195], v140 offset:17408
	ds_read_b128 v[196:199], v139 offset:16384
	ds_read_b128 v[200:203], v139 offset:17408
	ds_read_b128 v[204:207], v138 offset:16384
	ds_read_b128 v[208:211], v138 offset:17408
	global_load_lds_dwordx4 v[230:231], off
	v_lshl_add_u64 v[230:231], v[248:249], 0, s[30:31]
	s_mov_b32 m0, s3
	s_nop 0
	global_load_lds_dwordx4 v[230:231], off
	s_barrier
	s_waitcnt lgkmcnt(0)
	s_setprio 3
	s_waitcnt lgkmcnt(0)
	v_mfma_f32_16x16x32_bf16 v[60:63], v[164:167], v[180:183], v[60:63]
	v_mfma_f32_16x16x32_bf16 v[56:59], v[172:175], v[180:183], v[56:59]
	v_mfma_f32_16x16x32_bf16 v[52:55], v[164:167], v[188:191], v[52:55]
	v_mfma_f32_16x16x32_bf16 v[48:51], v[172:175], v[188:191], v[48:51]
	v_mfma_f32_16x16x32_bf16 v[44:47], v[164:167], v[196:199], v[44:47]
	v_mfma_f32_16x16x32_bf16 v[40:43], v[172:175], v[196:199], v[40:43]
	v_mfma_f32_16x16x32_bf16 v[36:39], v[164:167], v[204:207], v[36:39]
	v_mfma_f32_16x16x32_bf16 v[32:35], v[172:175], v[204:207], v[32:35]
	v_mfma_f32_16x16x32_bf16 v[60:63], v[168:171], v[184:187], v[60:63]
	v_mfma_f32_16x16x32_bf16 v[56:59], v[176:179], v[184:187], v[56:59]
	v_mfma_f32_16x16x32_bf16 v[52:55], v[168:171], v[192:195], v[52:55]
	v_mfma_f32_16x16x32_bf16 v[48:51], v[176:179], v[192:195], v[48:51]
	v_mfma_f32_16x16x32_bf16 v[44:47], v[168:171], v[200:203], v[44:47]
	v_mfma_f32_16x16x32_bf16 v[40:43], v[176:179], v[200:203], v[40:43]
	v_mfma_f32_16x16x32_bf16 v[36:39], v[168:171], v[208:211], v[36:39]
	v_mfma_f32_16x16x32_bf16 v[32:35], v[176:179], v[208:211], v[32:35]
	s_setprio 0
	s_barrier
; #define STAGE8(P, BASE, br, kt) do { const bf16_t* _g = (BASE) + (size_t)(br) * K + (kt) * 64; \
;     _Pragma("unroll") for (int _i = 0; _i < 2; ++_i) \
;       __builtin_amdgcn_global_load_lds((glb_u32*)(_g + goff0 + _i * 64 * K), (lds_u32*)((char*)(P) + tid * 16 + _i * 8192), 16, 0, 0); } while (0)
; #define LDA8(dst, b, h) _Pragma("unroll") for (int m = 0; m < 4; ++m) _Pragma("unroll") for (int k = 0; k < 2; ++k) \
;     dst[m][k] = *reinterpret_cast<const bf16x8*>((const char*)SA8(b, h) + lds_byte(wr * 64 + m * 16 + fr, k * 32 + fq * 8))
; #define LDB8(dst, b, h) _Pragma("unroll") for (int n = 0; n < 2; ++n) _Pragma("unroll") for (int k = 0; k < 2; ++k) \
;     dst[n][k] = *reinterpret_cast<const bf16x8*>((const char*)SB8(b, h) + lds_byte(wc * 32 + n * 16 + fr, k * 32 + fq * 8))
; #define MMA8(ai, bj, Af, Bf) do { __builtin_amdgcn_s_setprio(3); \
;     _Pragma("unroll") for (int m = 0; m < 4; ++m) _Pragma("unroll") for (int n = 0; n < 2; ++n) _Pragma("unroll") for (int k = 0; k < 2; ++k) \
;       acc[ai][bj][m][n] = __builtin_amdgcn_mfma_f32_16x16x32_bf16(Af[m][k], Bf[n][k], acc[ai][bj][m][n], 0, 0, 0); \
;     __builtin_amdgcn_s_setprio(0); } while (0)
; #define WAIT_V8(n) asm volatile("s_waitcnt vmcnt(" #n ")" ::: "memory")
; #define WAIT_L8(n) asm volatile("s_waitcnt lgkmcnt(" #n ")" ::: "memory")
; #define BAR8 __builtin_amdgcn_s_barrier()
; #define SCHED8 __builtin_amdgcn_sched_barrier(0)
; template <int EPI>
; __device__ __forceinline__ void gemm_tile8p(const bf16_t* __restrict__ Ag, const bf16_t* __restrict__ Bg, int K, int nt, int brow, int bcol,
;                                             char* smem, void* outp, int ldo, int nvalid, int rowoff, int rowlim) {
;     ...
;     WAIT_V8(6); BAR8; MMA8(1, 1, At, B1); BAR8;
;     LDB8(B0, 1, 0); SCHED8; LDA8(At, 1, 0); STAGE8(SA8(0, 1), Ag, brow + HALF, t + 2);
;     WAIT_L8(8); BAR8; WAIT_L8(0); MMA8(0, 0, At, B0); BAR8; SCHED8;
;     LDB8(B1, 1, 1); STAGE8(SB8(1, 0), Bg, bcol, t + 3);
;     BAR8; WAIT_L8(0); MMA8(0, 1, At, B1); BAR8;
;     LDA8(At, 1, 1); STAGE8(SA8(1, 0), Ag, brow, t + 3);
	v_readfirstlane_b32 s3, v147
	v_lshl_add_u64 v[164:165], v[250:251], 0, s[34:35]
	s_mov_b32 m0, s3
	v_readfirstlane_b32 s3, v148
	global_load_lds_dwordx4 v[164:165], off
	v_lshl_add_u64 v[164:165], v[250:251], 0, s[44:45]
	s_mov_b32 m0, s3
	s_nop 0
	global_load_lds_dwordx4 v[164:165], off
	s_waitcnt vmcnt(6)
	s_barrier
	s_setprio 3
	v_mfma_f32_16x16x32_bf16 v[28:31], v[232:235], v[180:183], v[28:31]
	v_mfma_f32_16x16x32_bf16 v[24:27], v[240:243], v[180:183], v[24:27]
	v_mfma_f32_16x16x32_bf16 v[20:23], v[232:235], v[188:191], v[20:23]
	v_mfma_f32_16x16x32_bf16 v[16:19], v[240:243], v[188:191], v[16:19]
	v_mfma_f32_16x16x32_bf16 v[12:15], v[232:235], v[196:199], v[12:15]
	v_mfma_f32_16x16x32_bf16 v[8:11], v[240:243], v[196:199], v[8:11]
	v_mfma_f32_16x16x32_bf16 v[4:7], v[232:235], v[204:207], v[4:7]
	v_mfma_f32_16x16x32_bf16 v[0:3], v[240:243], v[204:207], v[0:3]
	v_mfma_f32_16x16x32_bf16 v[28:31], v[236:239], v[184:187], v[28:31]
	v_mfma_f32_16x16x32_bf16 v[24:27], v[244:247], v[184:187], v[24:27]
	v_mfma_f32_16x16x32_bf16 v[20:23], v[236:239], v[192:195], v[20:23]
	v_mfma_f32_16x16x32_bf16 v[16:19], v[244:247], v[192:195], v[16:19]
	v_mfma_f32_16x16x32_bf16 v[12:15], v[236:239], v[200:203], v[12:15]
	v_mfma_f32_16x16x32_bf16 v[8:11], v[244:247], v[200:203], v[8:11]
	v_mfma_f32_16x16x32_bf16 v[4:7], v[236:239], v[208:211], v[4:7]
	v_mfma_f32_16x16x32_bf16 v[0:3], v[244:247], v[208:211], v[0:3]
	s_setprio 0
	s_barrier
	ds_read_b128 v[164:167], v146
	ds_read_b128 v[168:171], v146 offset:1024
	ds_read_b128 v[172:175], v146 offset:2048
	ds_read_b128 v[176:179], v146 offset:3072
	v_readfirstlane_b32 s3, v152
	v_lshl_add_u64 v[230:231], v[248:249], 0, s[50:51]
	s_mov_b32 m0, s3
	v_readfirstlane_b32 s3, v153
	ds_read_b128 v[180:183], v141 offset:32768
	ds_read_b128 v[184:187], v141 offset:33792
	ds_read_b128 v[188:191], v140 offset:32768
	ds_read_b128 v[192:195], v140 offset:33792
	ds_read_b128 v[196:199], v139 offset:32768
	ds_read_b128 v[200:203], v139 offset:33792
	ds_read_b128 v[204:207], v138 offset:32768
	ds_read_b128 v[208:211], v138 offset:33792
	global_load_lds_dwordx4 v[230:231], off
	v_lshl_add_u64 v[230:231], v[248:249], 0, s[54:55]
	s_mov_b32 m0, s3
	s_nop 0
	global_load_lds_dwordx4 v[230:231], off
	s_waitcnt lgkmcnt(8)
	s_barrier
	s_waitcnt lgkmcnt(0)
	s_setprio 3
	s_waitcnt lgkmcnt(0)
	v_mfma_f32_16x16x32_bf16 v[124:127], v[164:167], v[180:183], v[124:127]
	v_mfma_f32_16x16x32_bf16 v[120:123], v[172:175], v[180:183], v[120:123]
	v_mfma_f32_16x16x32_bf16 v[116:119], v[164:167], v[188:191], v[116:119]
	v_mfma_f32_16x16x32_bf16 v[112:115], v[172:175], v[188:191], v[112:115]
	v_mfma_f32_16x16x32_bf16 v[108:111], v[164:167], v[196:199], v[108:111]
	v_mfma_f32_16x16x32_bf16 v[104:107], v[172:175], v[196:199], v[104:107]
	v_mfma_f32_16x16x32_bf16 v[100:103], v[164:167], v[204:207], v[100:103]
	v_mfma_f32_16x16x32_bf16 v[96:99], v[172:175], v[204:207], v[96:99]
	v_mfma_f32_16x16x32_bf16 v[124:127], v[168:171], v[184:187], v[124:127]
	v_mfma_f32_16x16x32_bf16 v[120:123], v[176:179], v[184:187], v[120:123]
	v_mfma_f32_16x16x32_bf16 v[116:119], v[168:171], v[192:195], v[116:119]
	v_mfma_f32_16x16x32_bf16 v[112:115], v[176:179], v[192:195], v[112:115]
	v_mfma_f32_16x16x32_bf16 v[108:111], v[168:171], v[200:203], v[108:111]
	v_mfma_f32_16x16x32_bf16 v[104:107], v[176:179], v[200:203], v[104:107]
	v_mfma_f32_16x16x32_bf16 v[100:103], v[168:171], v[208:211], v[100:103]
	v_mfma_f32_16x16x32_bf16 v[96:99], v[176:179], v[208:211], v[96:99]
	s_setprio 0
	s_barrier
	v_readfirstlane_b32 s3, v154
	v_lshl_add_u64 v[230:231], v[250:251], 0, s[56:57]
	s_mov_b32 m0, s3
	v_readfirstlane_b32 s3, v155
	ds_read_b128 v[232:235], v144
	ds_read_b128 v[236:239], v144 offset:1024
	ds_read_b128 v[240:243], v144 offset:2048
	ds_read_b128 v[244:247], v144 offset:3072
	global_load_lds_dwordx4 v[230:231], off
	v_lshl_add_u64 v[230:231], v[250:251], 0, s[58:59]
	s_mov_b32 m0, s3
	s_nop 0
	global_load_lds_dwordx4 v[230:231], off
	s_barrier
	s_waitcnt lgkmcnt(0)
	s_setprio 3
	s_waitcnt lgkmcnt(0)
	v_mfma_f32_16x16x32_bf16 v[92:95], v[232:235], v[180:183], v[92:95]
	v_mfma_f32_16x16x32_bf16 v[88:91], v[240:243], v[180:183], v[88:91]
	v_mfma_f32_16x16x32_bf16 v[84:87], v[232:235], v[188:191], v[84:87]
	v_mfma_f32_16x16x32_bf16 v[80:83], v[240:243], v[188:191], v[80:83]
	v_mfma_f32_16x16x32_bf16 v[76:79], v[232:235], v[196:199], v[76:79]
	v_mfma_f32_16x16x32_bf16 v[72:75], v[240:243], v[196:199], v[72:75]
	v_mfma_f32_16x16x32_bf16 v[68:71], v[232:235], v[204:207], v[68:71]
	v_mfma_f32_16x16x32_bf16 v[64:67], v[240:243], v[204:207], v[64:67]
	v_mfma_f32_16x16x32_bf16 v[92:95], v[236:239], v[184:187], v[92:95]
	v_mfma_f32_16x16x32_bf16 v[88:91], v[244:247], v[184:187], v[88:91]
	v_mfma_f32_16x16x32_bf16 v[84:87], v[236:239], v[192:195], v[84:87]
	v_mfma_f32_16x16x32_bf16 v[80:83], v[244:247], v[192:195], v[80:83]
	v_mfma_f32_16x16x32_bf16 v[76:79], v[236:239], v[200:203], v[76:79]
	v_mfma_f32_16x16x32_bf16 v[72:75], v[244:247], v[200:203], v[72:75]
	v_mfma_f32_16x16x32_bf16 v[68:71], v[236:239], v[208:211], v[68:71]
	v_mfma_f32_16x16x32_bf16 v[64:67], v[244:247], v[208:211], v[64:67]
	s_setprio 0
	v_readfirstlane_b32 s3, v156
	v_lshl_add_u64 v[230:231], v[248:249], 0, s[64:65]
	s_mov_b32 m0, s3
	v_readfirstlane_b32 s3, v157
	s_barrier
	ds_read_b128 v[180:183], v141 offset:49152
	ds_read_b128 v[184:187], v141 offset:50176
	ds_read_b128 v[188:191], v140 offset:49152
	ds_read_b128 v[192:195], v140 offset:50176
	ds_read_b128 v[196:199], v139 offset:49152
	ds_read_b128 v[200:203], v139 offset:50176
	ds_read_b128 v[204:207], v138 offset:49152
	ds_read_b128 v[208:211], v138 offset:50176
	global_load_lds_dwordx4 v[230:231], off
	v_lshl_add_u64 v[230:231], v[248:249], 0, s[74:75]
	s_mov_b32 m0, s3
	s_nop 0
	global_load_lds_dwordx4 v[230:231], off
	s_barrier
; #define STAGE8(P, BASE, br, kt) do { const bf16_t* _g = (BASE) + (size_t)(br) * K + (kt) * 64; \
;     _Pragma("unroll") for (int _i = 0; _i < 2; ++_i) \
;       __builtin_amdgcn_global_load_lds((glb_u32*)(_g + goff0 + _i * 64 * K), (lds_u32*)((char*)(P) + tid * 16 + _i * 8192), 16, 0, 0); } while (0)
; #define LDA8(dst, b, h) _Pragma("unroll") for (int m = 0; m < 4; ++m) _Pragma("unroll") for (int k = 0; k < 2; ++k) \
;     dst[m][k] = *reinterpret_cast<const bf16x8*>((const char*)SA8(b, h) + lds_byte(wr * 64 + m * 16 + fr, k * 32 + fq * 8))
; #define LDB8(dst, b, h) _Pragma("unroll") for (int n = 0; n < 2; ++n) _Pragma("unroll") for (int k = 0; k < 2; ++k) \
;     dst[n][k] = *reinterpret_cast<const bf16x8*>((const char*)SB8(b, h) + lds_byte(wc * 32 + n * 16 + fr, k * 32 + fq * 8))
; #define MMA8(ai, bj, Af, Bf) do { __builtin_amdgcn_s_setprio(3); \
;     _Pragma("unroll") for (int m = 0; m < 4; ++m) _Pragma("unroll") for (int n = 0; n < 2; ++n) _Pragma("unroll") for (int k = 0; k < 2; ++k) \
;       acc[ai][bj][m][n] = __builtin_amdgcn_mfma_f32_16x16x32_bf16(Af[m][k], Bf[n][k], acc[ai][bj][m][n], 0, 0, 0); \
;     __builtin_amdgcn_s_setprio(0); } while (0)
; #define WAIT_V8(n) asm volatile("s_waitcnt vmcnt(" #n ")" ::: "memory")
; #define WAIT_L8(n) asm volatile("s_waitcnt lgkmcnt(" #n ")" ::: "memory")
; #define BAR8 __builtin_amdgcn_s_barrier()
; template <int EPI>
; __device__ __forceinline__ void gemm_tile8p(const bf16_t* __restrict__ Ag, const bf16_t* __restrict__ Bg, int K, int nt, int brow, int bcol,
;                                             char* smem, void* outp, int ldo, int nvalid, int rowoff, int rowlim) {
;     ...
;     WAIT_V8(6); BAR8; MMA8(1, 1, At, B1); BAR8;
;     LDB8(B0, 1, 0); SCHED8; LDA8(At, 1, 0); STAGE8(SA8(0, 1), Ag, brow + HALF, t + 2);
;     WAIT_L8(8); BAR8; WAIT_L8(0); MMA8(0, 0, At, B0); BAR8; SCHED8;
;     LDB8(B1, 1, 1); STAGE8(SB8(1, 0), Bg, bcol, t + 3);
;     BAR8; WAIT_L8(0); MMA8(0, 1, At, B1); BAR8;
;     LDA8(At, 1, 1); STAGE8(SA8(1, 0), Ag, brow, t + 3);
;     BAR8; WAIT_L8(0); MMA8(1, 0, At, B0); BAR8; SCHED8;
;     STAGE8(SB8(1, 1), Bg, bcol + HALF, t + 3);
;     WAIT_V8(6); BAR8; MMA8(1, 1, At, B1); BAR8;
;   }
;   { LDB8(B0, 0, 0); LDA8(At, 0, 0); STAGE8(SA8(1, 1), Ag, brow + HALF, nt - 1);
;     BAR8; WAIT_L8(0); MMA8(0, 0, At, B0); BAR8;
;     LDB8(B1, 0, 1); BAR8; WAIT_L8(0); MMA8(0, 1, At, B1); BAR8;
	s_waitcnt lgkmcnt(0)
	s_setprio 3
	s_waitcnt lgkmcnt(0)
	v_mfma_f32_16x16x32_bf16 v[60:63], v[164:167], v[180:183], v[60:63]
	v_mfma_f32_16x16x32_bf16 v[56:59], v[172:175], v[180:183], v[56:59]
	v_mfma_f32_16x16x32_bf16 v[52:55], v[164:167], v[188:191], v[52:55]
	v_mfma_f32_16x16x32_bf16 v[48:51], v[172:175], v[188:191], v[48:51]
	v_mfma_f32_16x16x32_bf16 v[44:47], v[164:167], v[196:199], v[44:47]
	v_mfma_f32_16x16x32_bf16 v[40:43], v[172:175], v[196:199], v[40:43]
	v_mfma_f32_16x16x32_bf16 v[36:39], v[164:167], v[204:207], v[36:39]
	v_mfma_f32_16x16x32_bf16 v[32:35], v[172:175], v[204:207], v[32:35]
	v_mfma_f32_16x16x32_bf16 v[60:63], v[168:171], v[184:187], v[60:63]
	v_mfma_f32_16x16x32_bf16 v[56:59], v[176:179], v[184:187], v[56:59]
	v_mfma_f32_16x16x32_bf16 v[52:55], v[168:171], v[192:195], v[52:55]
	v_mfma_f32_16x16x32_bf16 v[48:51], v[176:179], v[192:195], v[48:51]
	v_mfma_f32_16x16x32_bf16 v[44:47], v[168:171], v[200:203], v[44:47]
	v_mfma_f32_16x16x32_bf16 v[40:43], v[176:179], v[200:203], v[40:43]
	v_mfma_f32_16x16x32_bf16 v[36:39], v[168:171], v[208:211], v[36:39]
	v_mfma_f32_16x16x32_bf16 v[32:35], v[176:179], v[208:211], v[32:35]
	s_setprio 0
	s_barrier
	v_readfirstlane_b32 s3, v159
	v_lshl_add_u64 v[164:165], v[250:251], 0, s[82:83]
	s_mov_b32 m0, s3
	v_readfirstlane_b32 s3, v160
	global_load_lds_dwordx4 v[164:165], off
	v_lshl_add_u64 v[164:165], v[250:251], 0, s[86:87]
	s_mov_b32 m0, s3
	s_nop 0
	global_load_lds_dwordx4 v[164:165], off
	s_waitcnt vmcnt(6)
	s_barrier
	s_setprio 3
	v_mfma_f32_16x16x32_bf16 v[28:31], v[232:235], v[180:183], v[28:31]
	v_mfma_f32_16x16x32_bf16 v[24:27], v[240:243], v[180:183], v[24:27]
	v_mfma_f32_16x16x32_bf16 v[20:23], v[232:235], v[188:191], v[20:23]
	v_mfma_f32_16x16x32_bf16 v[16:19], v[240:243], v[188:191], v[16:19]
	v_mfma_f32_16x16x32_bf16 v[12:15], v[232:235], v[196:199], v[12:15]
	v_mfma_f32_16x16x32_bf16 v[8:11], v[240:243], v[196:199], v[8:11]
	v_mfma_f32_16x16x32_bf16 v[4:7], v[232:235], v[204:207], v[4:7]
	v_mfma_f32_16x16x32_bf16 v[0:3], v[240:243], v[204:207], v[0:3]
	v_mfma_f32_16x16x32_bf16 v[28:31], v[236:239], v[184:187], v[28:31]
	v_mfma_f32_16x16x32_bf16 v[24:27], v[244:247], v[184:187], v[24:27]
	v_mfma_f32_16x16x32_bf16 v[20:23], v[236:239], v[192:195], v[20:23]
	v_mfma_f32_16x16x32_bf16 v[16:19], v[244:247], v[192:195], v[16:19]
	v_mfma_f32_16x16x32_bf16 v[12:15], v[236:239], v[200:203], v[12:15]
	v_mfma_f32_16x16x32_bf16 v[8:11], v[244:247], v[200:203], v[8:11]
	v_mfma_f32_16x16x32_bf16 v[4:7], v[236:239], v[208:211], v[4:7]
	v_mfma_f32_16x16x32_bf16 v[0:3], v[244:247], v[208:211], v[0:3]
	s_setprio 0
	s_add_i32 s2, s2, 2
	s_add_u32 s40, s40, 0x100
	s_addc_u32 s41, s41, 0
	s_add_u32 s42, s42, 0x100
	s_addc_u32 s43, s43, 0
	s_cmp_lt_u32 s2, 12
	s_barrier
	s_cbranch_scc1 .LBB0_1066
	s_mov_b64 s[2:3], 0x780
	v_lshl_add_u64 v[130:131], v[128:129], 0, s[2:3]
	v_readfirstlane_b32 s2, v162
	s_mov_b32 m0, s2
	s_mov_b64 s[2:3], 0x20780
	v_lshl_add_u64 v[128:129], v[128:129], 0, s[2:3]
	v_readfirstlane_b32 s2, v163
	ds_read_b128 v[152:155], v161
	ds_read_b128 v[164:167], v161 offset:1024
	ds_read_b128 v[168:171], v161 offset:2048
	ds_read_b128 v[172:175], v161 offset:3072
	ds_read_b128 v[176:179], v141
	ds_read_b128 v[180:183], v141 offset:1024
	ds_read_b128 v[184:187], v140
	ds_read_b128 v[188:191], v140 offset:1024
	ds_read_b128 v[192:195], v139
	ds_read_b128 v[196:199], v139 offset:1024
	ds_read_b128 v[200:203], v138
	ds_read_b128 v[204:207], v138 offset:1024
	global_load_lds_dwordx4 v[130:131], off
	s_mov_b32 m0, s2
	s_nop 0
	global_load_lds_dwordx4 v[128:129], off
	s_barrier
	s_waitcnt lgkmcnt(0)
	s_setprio 3
	s_waitcnt lgkmcnt(0)
	v_mfma_f32_16x16x32_bf16 v[124:127], v[152:155], v[176:179], v[124:127]
	v_mfma_f32_16x16x32_bf16 v[120:123], v[168:171], v[176:179], v[120:123]
	v_mfma_f32_16x16x32_bf16 v[112:115], v[168:171], v[184:187], v[112:115]
	v_mfma_f32_16x16x32_bf16 v[104:107], v[168:171], v[192:195], v[104:107]
	v_mfma_f32_16x16x32_bf16 v[96:99], v[168:171], v[200:203], v[96:99]
	v_mfma_f32_16x16x32_bf16 v[124:127], v[164:167], v[180:183], v[124:127]
	v_mfma_f32_16x16x32_bf16 v[120:123], v[172:175], v[180:183], v[120:123]
	v_mfma_f32_16x16x32_bf16 v[116:119], v[152:155], v[184:187], v[116:119]
	v_mfma_f32_16x16x32_bf16 v[112:115], v[172:175], v[188:191], v[112:115]
	v_mfma_f32_16x16x32_bf16 v[108:111], v[152:155], v[192:195], v[108:111]
	v_mfma_f32_16x16x32_bf16 v[104:107], v[172:175], v[196:199], v[104:107]
	v_mfma_f32_16x16x32_bf16 v[100:103], v[152:155], v[200:203], v[100:103]
	v_mfma_f32_16x16x32_bf16 v[96:99], v[172:175], v[204:207], v[96:99]
	v_mfma_f32_16x16x32_bf16 v[128:131], v[164:167], v[188:191], v[116:119]
	v_mfma_f32_16x16x32_bf16 v[160:163], v[164:167], v[196:199], v[108:111]
	v_mfma_f32_16x16x32_bf16 v[208:211], v[164:167], v[204:207], v[100:103]
	s_setprio 0
	s_barrier
	s_nop 1
	ds_read_b128 v[100:103], v158
	ds_read_b128 v[108:111], v158 offset:1024
	ds_read_b128 v[116:119], v158 offset:2048
	ds_read_b128 v[156:159], v158 offset:3072
	s_barrier
	s_waitcnt lgkmcnt(0)
	s_setprio 3
	s_waitcnt lgkmcnt(0)
	v_mfma_f32_16x16x32_bf16 v[88:91], v[116:119], v[176:179], v[88:91]
	v_mfma_f32_16x16x32_bf16 v[80:83], v[116:119], v[184:187], v[80:83]
	v_mfma_f32_16x16x32_bf16 v[72:75], v[116:119], v[192:195], v[72:75]
	v_mfma_f32_16x16x32_bf16 v[64:67], v[116:119], v[200:203], v[64:67]
	v_mfma_f32_16x16x32_bf16 v[92:95], v[100:103], v[176:179], v[92:95]
	v_mfma_f32_16x16x32_bf16 v[88:91], v[156:159], v[180:183], v[88:91]
	v_mfma_f32_16x16x32_bf16 v[84:87], v[100:103], v[184:187], v[84:87]
	v_mfma_f32_16x16x32_bf16 v[80:83], v[156:159], v[188:191], v[80:83]
	v_mfma_f32_16x16x32_bf16 v[76:79], v[100:103], v[192:195], v[76:79]
	v_mfma_f32_16x16x32_bf16 v[72:75], v[156:159], v[196:199], v[72:75]
	v_mfma_f32_16x16x32_bf16 v[68:71], v[100:103], v[200:203], v[68:71]
	v_mfma_f32_16x16x32_bf16 v[64:67], v[156:159], v[204:207], v[64:67]
	v_mfma_f32_16x16x32_bf16 v[232:235], v[108:111], v[180:183], v[92:95]
	v_mfma_f32_16x16x32_bf16 v[176:179], v[108:111], v[188:191], v[84:87]
	v_mfma_f32_16x16x32_bf16 v[180:183], v[108:111], v[196:199], v[76:79]
	v_mfma_f32_16x16x32_bf16 v[184:187], v[108:111], v[204:207], v[68:71]
	s_setprio 0
	s_barrier
; #define LDA8(dst, b, h) _Pragma("unroll") for (int m = 0; m < 4; ++m) _Pragma("unroll") for (int k = 0; k < 2; ++k) \
;     dst[m][k] = *reinterpret_cast<const bf16x8*>((const char*)SA8(b, h) + lds_byte(wr * 64 + m * 16 + fr, k * 32 + fq * 8))
; #define LDB8(dst, b, h) _Pragma("unroll") for (int n = 0; n < 2; ++n) _Pragma("unroll") for (int k = 0; k < 2; ++k) \
;     dst[n][k] = *reinterpret_cast<const bf16x8*>((const char*)SB8(b, h) + lds_byte(wc * 32 + n * 16 + fr, k * 32 + fq * 8))
; #define MMA8(ai, bj, Af, Bf) do { __builtin_amdgcn_s_setprio(3); \
;     _Pragma("unroll") for (int m = 0; m < 4; ++m) _Pragma("unroll") for (int n = 0; n < 2; ++n) _Pragma("unroll") for (int k = 0; k < 2; ++k) \
;       acc[ai][bj][m][n] = __builtin_amdgcn_mfma_f32_16x16x32_bf16(Af[m][k], Bf[n][k], acc[ai][bj][m][n], 0, 0, 0); \
;     __builtin_amdgcn_s_setprio(0); } while (0)
; #define WAIT_V8(n) asm volatile("s_waitcnt vmcnt(" #n ")" ::: "memory")
; #define WAIT_L8(n) asm volatile("s_waitcnt lgkmcnt(" #n ")" ::: "memory")
; #define BAR8 __builtin_amdgcn_s_barrier()
; template <int EPI>
; __device__ __forceinline__ void gemm_tile8p(const bf16_t* __restrict__ Ag, const bf16_t* __restrict__ Bg, int K, int nt, int brow, int bcol,
;                                             char* smem, void* outp, int ldo, int nvalid, int rowoff, int rowlim) {
;     ...
;     LDA8(At, 0, 1); WAIT_V8(4); BAR8; WAIT_L8(0); MMA8(1, 0, At, B0); MMA8(1, 1, At, B1); BAR8; }
;   { LDB8(B0, 1, 0); LDA8(At, 1, 0); WAIT_V8(2); BAR8; WAIT_L8(0); MMA8(0, 0, At, B0); BAR8;
;     LDB8(B1, 1, 1); WAIT_V8(0); BAR8; WAIT_L8(0); MMA8(0, 1, At, B1); BAR8;
	s_nop 0
	ds_read_b128 v[68:71], v141 offset:16384
	ds_read_b128 v[76:79], v141 offset:17408
	ds_read_b128 v[84:87], v140 offset:16384
	ds_read_b128 v[92:95], v140 offset:17408
	ds_read_b128 v[188:191], v139 offset:16384
	ds_read_b128 v[192:195], v139 offset:17408
	ds_read_b128 v[196:199], v138 offset:16384
	ds_read_b128 v[200:203], v138 offset:17408
	s_waitcnt vmcnt(4)
	s_barrier
	s_waitcnt lgkmcnt(0)
	s_setprio 3
	s_waitcnt lgkmcnt(0)
	v_mfma_f32_16x16x32_bf16 v[60:63], v[152:155], v[68:71], v[60:63]
	v_mfma_f32_16x16x32_bf16 v[56:59], v[168:171], v[68:71], v[56:59]
	v_mfma_f32_16x16x32_bf16 v[48:51], v[168:171], v[84:87], v[48:51]
	v_mfma_f32_16x16x32_bf16 v[40:43], v[168:171], v[188:191], v[40:43]
	v_mfma_f32_16x16x32_bf16 v[32:35], v[168:171], v[196:199], v[32:35]
	v_mfma_f32_16x16x32_bf16 v[60:63], v[164:167], v[76:79], v[60:63]
	v_mfma_f32_16x16x32_bf16 v[56:59], v[172:175], v[76:79], v[56:59]
	v_mfma_f32_16x16x32_bf16 v[52:55], v[152:155], v[84:87], v[52:55]
	v_mfma_f32_16x16x32_bf16 v[48:51], v[172:175], v[92:95], v[48:51]
	v_mfma_f32_16x16x32_bf16 v[44:47], v[152:155], v[188:191], v[44:47]
	v_mfma_f32_16x16x32_bf16 v[40:43], v[172:175], v[192:195], v[40:43]
	v_mfma_f32_16x16x32_bf16 v[36:39], v[152:155], v[196:199], v[36:39]
	v_mfma_f32_16x16x32_bf16 v[32:35], v[172:175], v[200:203], v[32:35]
	v_mfma_f32_16x16x32_bf16 v[204:207], v[164:167], v[92:95], v[52:55]
	v_mfma_f32_16x16x32_bf16 v[236:239], v[164:167], v[192:195], v[44:47]
	v_mfma_f32_16x16x32_bf16 v[152:155], v[164:167], v[200:203], v[36:39]
	s_setprio 0
	s_setprio 3
	v_mfma_f32_16x16x32_bf16 v[24:27], v[116:119], v[68:71], v[24:27]
	v_mfma_f32_16x16x32_bf16 v[16:19], v[116:119], v[84:87], v[16:19]
	v_mfma_f32_16x16x32_bf16 v[4:7], v[100:103], v[196:199], v[4:7]
	v_mfma_f32_16x16x32_bf16 v[0:3], v[116:119], v[196:199], v[0:3]
	v_mfma_f32_16x16x32_bf16 v[28:31], v[100:103], v[68:71], v[28:31]
	v_mfma_f32_16x16x32_bf16 v[24:27], v[156:159], v[76:79], v[24:27]
	v_mfma_f32_16x16x32_bf16 v[20:23], v[100:103], v[84:87], v[20:23]
	v_mfma_f32_16x16x32_bf16 v[16:19], v[156:159], v[92:95], v[16:19]
	v_mfma_f32_16x16x32_bf16 v[12:15], v[100:103], v[188:191], v[12:15]
	v_mfma_f32_16x16x32_bf16 v[8:11], v[116:119], v[188:191], v[8:11]
	v_mfma_f32_16x16x32_bf16 v[4:7], v[108:111], v[200:203], v[4:7]
	v_mfma_f32_16x16x32_bf16 v[0:3], v[156:159], v[200:203], v[0:3]
	v_mfma_f32_16x16x32_bf16 v[164:167], v[108:111], v[76:79], v[28:31]
	v_mfma_f32_16x16x32_bf16 v[168:171], v[108:111], v[92:95], v[20:23]
	v_mfma_f32_16x16x32_bf16 v[172:175], v[108:111], v[192:195], v[12:15]
	v_mfma_f32_16x16x32_bf16 v[188:191], v[156:159], v[192:195], v[8:11]
	s_setprio 0
	s_barrier
	s_nop 0
	ds_read_b128 v[8:11], v146
	ds_read_b128 v[12:15], v146 offset:1024
	ds_read_b128 v[156:159], v146 offset:2048
	ds_read_b128 v[192:195], v146 offset:3072
	ds_read_b128 v[20:23], v141 offset:32768
	ds_read_b128 v[28:31], v141 offset:33792
	ds_read_b128 v[36:39], v140 offset:32768
	ds_read_b128 v[44:47], v140 offset:33792
	ds_read_b128 v[52:55], v139 offset:32768
	ds_read_b128 v[196:199], v139 offset:33792
	ds_read_b128 v[200:203], v138 offset:32768
	ds_read_b128 v[240:243], v138 offset:33792
	s_waitcnt vmcnt(2)
	s_barrier
	s_waitcnt lgkmcnt(0)
	s_setprio 3
	s_waitcnt lgkmcnt(0)
	v_mfma_f32_16x16x32_bf16 v[68:71], v[8:11], v[20:23], v[124:127]
	v_mfma_f32_16x16x32_bf16 v[124:127], v[12:15], v[28:31], v[68:71]
	v_mfma_f32_16x16x32_bf16 v[68:71], v[156:159], v[20:23], v[120:123]
	v_mfma_f32_16x16x32_bf16 v[116:119], v[192:195], v[28:31], v[68:71]
	v_mfma_f32_16x16x32_bf16 v[68:71], v[8:11], v[36:39], v[128:131]
	v_mfma_f32_16x16x32_bf16 v[108:111], v[12:15], v[44:47], v[68:71]
	v_mfma_f32_16x16x32_bf16 v[68:71], v[156:159], v[36:39], v[112:115]
	v_mfma_f32_16x16x32_bf16 v[100:103], v[192:195], v[44:47], v[68:71]
	v_mfma_f32_16x16x32_bf16 v[68:71], v[8:11], v[52:55], v[160:163]
	v_mfma_f32_16x16x32_bf16 v[92:95], v[12:15], v[196:199], v[68:71]
	v_mfma_f32_16x16x32_bf16 v[68:71], v[156:159], v[52:55], v[104:107]
	v_mfma_f32_16x16x32_bf16 v[84:87], v[192:195], v[196:199], v[68:71]
	v_mfma_f32_16x16x32_bf16 v[68:71], v[8:11], v[200:203], v[208:211]
	v_mfma_f32_16x16x32_bf16 v[76:79], v[12:15], v[240:243], v[68:71]
	v_mfma_f32_16x16x32_bf16 v[68:71], v[156:159], v[200:203], v[96:99]
	v_mfma_f32_16x16x32_bf16 v[68:71], v[192:195], v[240:243], v[68:71]
	s_setprio 0
	s_barrier
	ds_read_b128 v[128:131], v144
	ds_read_b128 v[160:163], v144 offset:1024
	ds_read_b128 v[208:211], v144 offset:2048
	ds_read_b128 v[142:145], v144 offset:3072
	s_waitcnt vmcnt(0)
	s_barrier
	s_waitcnt lgkmcnt(0)
	s_setprio 3
	s_waitcnt lgkmcnt(0)
	v_mfma_f32_16x16x32_bf16 v[96:99], v[128:131], v[20:23], v[232:235]
	v_mfma_f32_16x16x32_bf16 v[20:23], v[208:211], v[20:23], v[88:91]
	v_mfma_f32_16x16x32_bf16 v[112:115], v[142:145], v[28:31], v[20:23]
	v_mfma_f32_16x16x32_bf16 v[20:23], v[128:131], v[36:39], v[176:179]
	v_mfma_f32_16x16x32_bf16 v[104:107], v[160:163], v[44:47], v[20:23]
	v_mfma_f32_16x16x32_bf16 v[20:23], v[208:211], v[36:39], v[80:83]
	v_mfma_f32_16x16x32_bf16 v[120:123], v[160:163], v[28:31], v[96:99]
	v_mfma_f32_16x16x32_bf16 v[96:99], v[142:145], v[44:47], v[20:23]
	v_mfma_f32_16x16x32_bf16 v[20:23], v[128:131], v[52:55], v[180:183]
	v_mfma_f32_16x16x32_bf16 v[88:91], v[160:163], v[196:199], v[20:23]
	v_mfma_f32_16x16x32_bf16 v[20:23], v[208:211], v[52:55], v[72:75]
	v_mfma_f32_16x16x32_bf16 v[80:83], v[142:145], v[196:199], v[20:23]
	v_mfma_f32_16x16x32_bf16 v[20:23], v[128:131], v[200:203], v[184:187]
	v_mfma_f32_16x16x32_bf16 v[72:75], v[160:163], v[240:243], v[20:23]
	v_mfma_f32_16x16x32_bf16 v[20:23], v[208:211], v[200:203], v[64:67]
	v_mfma_f32_16x16x32_bf16 v[64:67], v[142:145], v[240:243], v[20:23]
	s_setprio 0
	s_barrier
; __device__ __forceinline__ bf16_t f2bf(float f) { return (bf16_t)(pack2(f, 0.f) & 0xffffu); }
; __device__ __forceinline__ float siluf_(float x) { return x * __builtin_amdgcn_rcpf(1.f + __expf(-x)); }
; #define LDA8(dst, b, h) _Pragma("unroll") for (int m = 0; m < 4; ++m) _Pragma("unroll") for (int k = 0; k < 2; ++k) \
;     dst[m][k] = *reinterpret_cast<const bf16x8*>((const char*)SA8(b, h) + lds_byte(wr * 64 + m * 16 + fr, k * 32 + fq * 8))
; #define MMA8(ai, bj, Af, Bf) do { __builtin_amdgcn_s_setprio(3); \
;     _Pragma("unroll") for (int m = 0; m < 4; ++m) _Pragma("unroll") for (int n = 0; n < 2; ++n) _Pragma("unroll") for (int k = 0; k < 2; ++k) \
;       acc[ai][bj][m][n] = __builtin_amdgcn_mfma_f32_16x16x32_bf16(Af[m][k], Bf[n][k], acc[ai][bj][m][n], 0, 0, 0); \
;     __builtin_amdgcn_s_setprio(0); } while (0)
; template <int EPI>
; __device__ __forceinline__ void gemm_tile8p(const bf16_t* __restrict__ Ag, const bf16_t* __restrict__ Bg, int K, int nt, int brow, int bcol,
;                                             char* smem, void* outp, int ldo, int nvalid, int rowoff, int rowlim) {
;     ...
;     LDA8(At, 1, 1); BAR8; WAIT_L8(0); MMA8(1, 0, At, B0); MMA8(1, 1, At, B1); BAR8; }
;   if (wr == 0) BAR8;
; #pragma unroll
;   for (int ai = 0; ai < 2; ++ai)
; #pragma unroll
;     for (int m = 0; m < 4; ++m)
; #pragma unroll
;       for (int j = 0; j < 4; ++j) {
;         const int rl = ai * HALF + wr * 64 + m * 16 + fq * 4 + j;
;         const size_t orow = (size_t)(rowoff + rl) * ldo;
;         if (EPI == EPI_GLU) {
; #pragma unroll
;           for (int n = 0; n < 2; ++n) {
;             const int col = (bcol >> 8) * 128 + wc * 32 + n * 16 + fr;
;             const float g = acc[ai][0][m][n][j], u = acc[ai][1][m][n][j];
;             if (rl < rowlim) ((bf16_t*)outp)[orow + col] = f2bf(siluf_(g) * u);
;           }
;         } else {
; #pragma unroll
;           for (int bj = 0; bj < 2; ++bj)
; #pragma unroll
;             for (int n = 0; n < 2; ++n) {
;               const int col = bcol + bj * HALF + wc * 32 + n * 16 + fr;
;               const float v = acc[ai][bj][m][n][j];
;               if (EPI == EPI_BF16) { if (rl < rowlim && col < nvalid) ((bf16_t*)outp)[orow + col] = f2bf(v); }
;               else { if (rl < rowlim) ((float*)outp)[orow + col] = v; }
;             }
;         }
;         __builtin_amdgcn_sched_barrier(0);
;       }
	ds_read_b128 v[176:179], v141 offset:49152
	ds_read_b128 v[180:183], v141 offset:50176
	ds_read_b128 v[184:187], v140 offset:49152
	ds_read_b128 v[196:199], v140 offset:50176
	ds_read_b128 v[200:203], v139 offset:49152
	ds_read_b128 v[232:235], v139 offset:50176
	ds_read_b128 v[240:243], v138 offset:49152
	ds_read_b128 v[138:141], v138 offset:50176
	s_barrier
	s_waitcnt lgkmcnt(0)
	s_setprio 3
	s_waitcnt lgkmcnt(0)
	v_mfma_f32_16x16x32_bf16 v[20:23], v[8:11], v[176:179], v[60:63]
	v_mfma_f32_16x16x32_bf16 v[60:63], v[12:15], v[180:183], v[20:23]
	v_mfma_f32_16x16x32_bf16 v[20:23], v[156:159], v[176:179], v[56:59]
	v_mfma_f32_16x16x32_bf16 v[52:55], v[192:195], v[180:183], v[20:23]
	v_mfma_f32_16x16x32_bf16 v[20:23], v[8:11], v[184:187], v[204:207]
	v_mfma_f32_16x16x32_bf16 v[44:47], v[12:15], v[196:199], v[20:23]
	v_mfma_f32_16x16x32_bf16 v[20:23], v[156:159], v[184:187], v[48:51]
	v_mfma_f32_16x16x32_bf16 v[36:39], v[192:195], v[196:199], v[20:23]
	v_mfma_f32_16x16x32_bf16 v[20:23], v[8:11], v[200:203], v[236:239]
	v_mfma_f32_16x16x32_bf16 v[8:11], v[8:11], v[240:243], v[152:155]
	v_mfma_f32_16x16x32_bf16 v[28:31], v[12:15], v[232:235], v[20:23]
	v_mfma_f32_16x16x32_bf16 v[20:23], v[156:159], v[200:203], v[40:43]
	v_mfma_f32_16x16x32_bf16 v[12:15], v[12:15], v[138:141], v[8:11]
	v_mfma_f32_16x16x32_bf16 v[8:11], v[156:159], v[240:243], v[32:35]
	v_mfma_f32_16x16x32_bf16 v[20:23], v[192:195], v[232:235], v[20:23]
	v_mfma_f32_16x16x32_bf16 v[8:11], v[192:195], v[138:141], v[8:11]
	s_setprio 0
	s_setprio 3
	v_mfma_f32_16x16x32_bf16 v[32:35], v[128:131], v[176:179], v[164:167]
	v_mfma_f32_16x16x32_bf16 v[24:27], v[208:211], v[176:179], v[24:27]
	v_mfma_f32_16x16x32_bf16 v[16:19], v[208:211], v[184:187], v[16:19]
	v_mfma_f32_16x16x32_bf16 v[56:59], v[160:163], v[180:183], v[32:35]
	v_mfma_f32_16x16x32_bf16 v[48:51], v[142:145], v[180:183], v[24:27]
	v_mfma_f32_16x16x32_bf16 v[24:27], v[128:131], v[184:187], v[168:171]
	v_mfma_f32_16x16x32_bf16 v[32:35], v[142:145], v[196:199], v[16:19]
	v_mfma_f32_16x16x32_bf16 v[16:19], v[128:131], v[200:203], v[172:175]
	v_mfma_f32_16x16x32_bf16 v[40:43], v[160:163], v[196:199], v[24:27]
	v_mfma_f32_16x16x32_bf16 v[24:27], v[160:163], v[232:235], v[16:19]
	v_mfma_f32_16x16x32_bf16 v[16:19], v[208:211], v[200:203], v[188:191]
	v_mfma_f32_16x16x32_bf16 v[4:7], v[128:131], v[240:243], v[4:7]
	v_mfma_f32_16x16x32_bf16 v[0:3], v[208:211], v[240:243], v[0:3]
	v_mfma_f32_16x16x32_bf16 v[16:19], v[142:145], v[232:235], v[16:19]
	v_mfma_f32_16x16x32_bf16 v[4:7], v[160:163], v[138:141], v[4:7]
	v_mfma_f32_16x16x32_bf16 v[0:3], v[142:145], v[138:141], v[0:3]
	s_setprio 0
	v_cmp_gt_u32_e32 vcc, s0, v132
	s_barrier
	s_and_saveexec_b64 s[2:3], vcc
	s_cbranch_execz .LBB0_1069
	s_barrier
.LBB0_1069:
	s_or_b64 exec, exec, s[2:3]
	s_sub_i32 s4, 0x4080, s48
	v_or_b32_e32 v160, v136, v134
	v_lshlrev_b32_e32 v162, 5, v133
	v_lshl_or_b32 v162, v135, 2, v162
	v_or_b32_e32 v162, s38, v162
	s_movk_i32 s0, 0xd04
	v_add_u32_e32 v161, 16, v162
	v_add_u32_e32 v166, 0x80, v162
	v_add_u32_e32 v167, 0x90, v162
	v_cmp_gt_i32_e64 s[38:39], s0, v162
	v_cmp_gt_i32_e64 s[40:41], s0, v161
	v_cmp_gt_i32_e64 s[42:43], s0, v166
	v_cmp_gt_i32_e64 s[44:45], s0, v167
	v_mov_b32_e32 v163, 0
	v_lshl_add_u64 v[164:165], v[162:163], 1, s[68:69]
	v_mov_b32_e32 v166, v160
	v_cmp_gt_i32_e64 s[2:3], s4, v166
	v_add_u32_e32 v166, s48, v166
	v_mad_u64_u32 v[168:169], vcc, v166, s72, v[164:165]
	v_cvt_pk_bf16_f32 v170, v124, v125
	v_cvt_pk_bf16_f32 v171, v126, v127
	v_cvt_pk_bf16_f32 v172, v116, v117
	v_cvt_pk_bf16_f32 v173, v118, v119
	v_cvt_pk_bf16_f32 v174, v120, v121
	v_cvt_pk_bf16_f32 v175, v122, v123
	v_cvt_pk_bf16_f32 v176, v112, v113
	v_cvt_pk_bf16_f32 v177, v114, v115
	s_and_b64 exec, s[2:3], s[38:39]
	global_store_dwordx2 v[168:169], v[170:171], off
	s_and_b64 exec, s[2:3], s[40:41]
	global_store_dwordx2 v[168:169], v[172:173], off offset:32
	s_and_b64 exec, s[2:3], s[42:43]
	global_store_dwordx2 v[168:169], v[174:175], off offset:256
	s_and_b64 exec, s[2:3], s[44:45]
	global_store_dwordx2 v[168:169], v[176:177], off offset:288
	s_mov_b64 exec, -1
	v_add_u32_e32 v166, 16, v160
	v_cmp_gt_i32_e64 s[2:3], s4, v166
	v_add_u32_e32 v166, s48, v166
	v_mad_u64_u32 v[168:169], vcc, v166, s72, v[164:165]
	v_cvt_pk_bf16_f32 v170, v108, v109
	v_cvt_pk_bf16_f32 v171, v110, v111
	v_cvt_pk_bf16_f32 v172, v100, v101
	v_cvt_pk_bf16_f32 v173, v102, v103
	v_cvt_pk_bf16_f32 v174, v104, v105
	v_cvt_pk_bf16_f32 v175, v106, v107
	v_cvt_pk_bf16_f32 v176, v96, v97
	v_cvt_pk_bf16_f32 v177, v98, v99
	s_and_b64 exec, s[2:3], s[38:39]
	global_store_dwordx2 v[168:169], v[170:171], off
	s_and_b64 exec, s[2:3], s[40:41]
	global_store_dwordx2 v[168:169], v[172:173], off offset:32
	s_and_b64 exec, s[2:3], s[42:43]
	global_store_dwordx2 v[168:169], v[174:175], off offset:256
	s_and_b64 exec, s[2:3], s[44:45]
	global_store_dwordx2 v[168:169], v[176:177], off offset:288
; __device__ __forceinline__ bf16_t f2bf(float f) { return (bf16_t)(pack2(f, 0.f) & 0xffffu); }
; __device__ __forceinline__ float siluf_(float x) { return x * __builtin_amdgcn_rcpf(1.f + __expf(-x)); }
; template <int EPI>
; __device__ __forceinline__ void gemm_tile8p(const bf16_t* __restrict__ Ag, const bf16_t* __restrict__ Bg, int K, int nt, int brow, int bcol,
;                                             char* smem, void* outp, int ldo, int nvalid, int rowoff, int rowlim) {
;     ...
; #pragma unroll
;   for (int ai = 0; ai < 2; ++ai)
; #pragma unroll
;     for (int m = 0; m < 4; ++m)
; #pragma unroll
;       for (int j = 0; j < 4; ++j) {
;         const int rl = ai * HALF + wr * 64 + m * 16 + fq * 4 + j;
;         const size_t orow = (size_t)(rowoff + rl) * ldo;
;         if (EPI == EPI_GLU) {
; #pragma unroll
;           for (int n = 0; n < 2; ++n) {
;             const int col = (bcol >> 8) * 128 + wc * 32 + n * 16 + fr;
;             const float g = acc[ai][0][m][n][j], u = acc[ai][1][m][n][j];
;             if (rl < rowlim) ((bf16_t*)outp)[orow + col] = f2bf(siluf_(g) * u);
;           }
;         } else {
; #pragma unroll
;           for (int bj = 0; bj < 2; ++bj)
; #pragma unroll
;             for (int n = 0; n < 2; ++n) {
;               const int col = bcol + bj * HALF + wc * 32 + n * 16 + fr;
;               const float v = acc[ai][bj][m][n][j];
;               if (EPI == EPI_BF16) { if (rl < rowlim && col < nvalid) ((bf16_t*)outp)[orow + col] = f2bf(v); }
;               else { if (rl < rowlim) ((float*)outp)[orow + col] = v; }
;             }
;         }
;         __builtin_amdgcn_sched_barrier(0);
;       }
	s_mov_b64 exec, -1
	v_add_u32_e32 v166, 32, v160
	v_cmp_gt_i32_e64 s[2:3], s4, v166
	v_add_u32_e32 v166, s48, v166
	v_mad_u64_u32 v[168:169], vcc, v166, s72, v[164:165]
	v_cvt_pk_bf16_f32 v170, v92, v93
	v_cvt_pk_bf16_f32 v171, v94, v95
	v_cvt_pk_bf16_f32 v172, v84, v85
	v_cvt_pk_bf16_f32 v173, v86, v87
	v_cvt_pk_bf16_f32 v174, v88, v89
	v_cvt_pk_bf16_f32 v175, v90, v91
	v_cvt_pk_bf16_f32 v176, v80, v81
	v_cvt_pk_bf16_f32 v177, v82, v83
	s_and_b64 exec, s[2:3], s[38:39]
	global_store_dwordx2 v[168:169], v[170:171], off
	s_and_b64 exec, s[2:3], s[40:41]
	global_store_dwordx2 v[168:169], v[172:173], off offset:32
	s_and_b64 exec, s[2:3], s[42:43]
	global_store_dwordx2 v[168:169], v[174:175], off offset:256
	s_and_b64 exec, s[2:3], s[44:45]
	global_store_dwordx2 v[168:169], v[176:177], off offset:288
	s_mov_b64 exec, -1
	v_add_u32_e32 v166, 48, v160
	v_cmp_gt_i32_e64 s[2:3], s4, v166
	v_add_u32_e32 v166, s48, v166
	v_mad_u64_u32 v[168:169], vcc, v166, s72, v[164:165]
	v_cvt_pk_bf16_f32 v170, v76, v77
	v_cvt_pk_bf16_f32 v171, v78, v79
	v_cvt_pk_bf16_f32 v172, v68, v69
	v_cvt_pk_bf16_f32 v173, v70, v71
	v_cvt_pk_bf16_f32 v174, v72, v73
	v_cvt_pk_bf16_f32 v175, v74, v75
	v_cvt_pk_bf16_f32 v176, v64, v65
	v_cvt_pk_bf16_f32 v177, v66, v67
	s_and_b64 exec, s[2:3], s[38:39]
	global_store_dwordx2 v[168:169], v[170:171], off
	s_and_b64 exec, s[2:3], s[40:41]
	global_store_dwordx2 v[168:169], v[172:173], off offset:32
	s_and_b64 exec, s[2:3], s[42:43]
	global_store_dwordx2 v[168:169], v[174:175], off offset:256
	s_and_b64 exec, s[2:3], s[44:45]
	global_store_dwordx2 v[168:169], v[176:177], off offset:288
	s_mov_b64 exec, -1
	v_add_u32_e32 v166, 128, v160
	v_cmp_gt_i32_e64 s[2:3], s4, v166
	v_add_u32_e32 v166, s48, v166
	v_mad_u64_u32 v[168:169], vcc, v166, s72, v[164:165]
	v_cvt_pk_bf16_f32 v170, v60, v61
	v_cvt_pk_bf16_f32 v171, v62, v63
	v_cvt_pk_bf16_f32 v172, v52, v53
	v_cvt_pk_bf16_f32 v173, v54, v55
	v_cvt_pk_bf16_f32 v174, v56, v57
	v_cvt_pk_bf16_f32 v175, v58, v59
	v_cvt_pk_bf16_f32 v176, v48, v49
	v_cvt_pk_bf16_f32 v177, v50, v51
	s_and_b64 exec, s[2:3], s[38:39]
	global_store_dwordx2 v[168:169], v[170:171], off
	s_and_b64 exec, s[2:3], s[40:41]
	global_store_dwordx2 v[168:169], v[172:173], off offset:32
	s_and_b64 exec, s[2:3], s[42:43]
	global_store_dwordx2 v[168:169], v[174:175], off offset:256
	s_and_b64 exec, s[2:3], s[44:45]
	global_store_dwordx2 v[168:169], v[176:177], off offset:288
	s_mov_b64 exec, -1
	v_add_u32_e32 v166, 144, v160
	v_cmp_gt_i32_e64 s[2:3], s4, v166
	v_add_u32_e32 v166, s48, v166
	v_mad_u64_u32 v[168:169], vcc, v166, s72, v[164:165]
	v_cvt_pk_bf16_f32 v170, v44, v45
	v_cvt_pk_bf16_f32 v171, v46, v47
	v_cvt_pk_bf16_f32 v172, v36, v37
	v_cvt_pk_bf16_f32 v173, v38, v39
	v_cvt_pk_bf16_f32 v174, v40, v41
	v_cvt_pk_bf16_f32 v175, v42, v43
	v_cvt_pk_bf16_f32 v176, v32, v33
	v_cvt_pk_bf16_f32 v177, v34, v35
	s_and_b64 exec, s[2:3], s[38:39]
	global_store_dwordx2 v[168:169], v[170:171], off
	s_and_b64 exec, s[2:3], s[40:41]
	global_store_dwordx2 v[168:169], v[172:173], off offset:32
	s_and_b64 exec, s[2:3], s[42:43]
	global_store_dwordx2 v[168:169], v[174:175], off offset:256
	s_and_b64 exec, s[2:3], s[44:45]
	global_store_dwordx2 v[168:169], v[176:177], off offset:288
	s_mov_b64 exec, -1
	v_add_u32_e32 v166, 160, v160
	v_cmp_gt_i32_e64 s[2:3], s4, v166
	v_add_u32_e32 v166, s48, v166
	v_mad_u64_u32 v[168:169], vcc, v166, s72, v[164:165]
	v_cvt_pk_bf16_f32 v170, v28, v29
	v_cvt_pk_bf16_f32 v171, v30, v31
	v_cvt_pk_bf16_f32 v172, v20, v21
	v_cvt_pk_bf16_f32 v173, v22, v23
	v_cvt_pk_bf16_f32 v174, v24, v25
	v_cvt_pk_bf16_f32 v175, v26, v27
	v_cvt_pk_bf16_f32 v176, v16, v17
	v_cvt_pk_bf16_f32 v177, v18, v19
	s_and_b64 exec, s[2:3], s[38:39]
	global_store_dwordx2 v[168:169], v[170:171], off
	s_and_b64 exec, s[2:3], s[40:41]
	global_store_dwordx2 v[168:169], v[172:173], off offset:32
	s_and_b64 exec, s[2:3], s[42:43]
	global_store_dwordx2 v[168:169], v[174:175], off offset:256
	s_and_b64 exec, s[2:3], s[44:45]
	global_store_dwordx2 v[168:169], v[176:177], off offset:288
	s_mov_b64 exec, -1
	v_add_u32_e32 v166, 176, v160
	v_cmp_gt_i32_e64 s[2:3], s4, v166
	v_add_u32_e32 v166, s48, v166
	v_mad_u64_u32 v[168:169], vcc, v166, s72, v[164:165]
	v_cvt_pk_bf16_f32 v170, v12, v13
	v_cvt_pk_bf16_f32 v171, v14, v15
	v_cvt_pk_bf16_f32 v172, v8, v9
	v_cvt_pk_bf16_f32 v173, v10, v11
	v_cvt_pk_bf16_f32 v174, v4, v5
	v_cvt_pk_bf16_f32 v175, v6, v7
	v_cvt_pk_bf16_f32 v176, v0, v1
	v_cvt_pk_bf16_f32 v177, v2, v3
	s_and_b64 exec, s[2:3], s[38:39]
	global_store_dwordx2 v[168:169], v[170:171], off
	s_and_b64 exec, s[2:3], s[40:41]
	global_store_dwordx2 v[168:169], v[172:173], off offset:32
	s_and_b64 exec, s[2:3], s[42:43]
	global_store_dwordx2 v[168:169], v[174:175], off offset:256
	s_and_b64 exec, s[2:3], s[44:45]
	global_store_dwordx2 v[168:169], v[176:177], off offset:288
	s_mov_b64 exec, -1
	s_branch .LBB0_1060
